# K-loops: one static s_setprio 1 for waves 0-3, no per-phase flips
# speedup vs baseline: 1.0006x; 1.0006x over previous
.LBB0_100:
	s_cmp_ge_u32 s9, 0x1000
	s_cbranch_scc1 .Lsp_0
	s_setprio 1

.LBB0_179:
	s_cmp_ge_u32 s73, 0x1000
	s_cbranch_scc1 .Lsp_1
	s_setprio 1

.LBB0_528:
	s_cmp_ge_u32 s3, 0x1000
	s_cbranch_scc1 .Lsp_2
	s_setprio 1

.LBB0_618:
	s_cmp_ge_u32 s11, 0x1000
	s_cbranch_scc1 .Lsp_3
	s_setprio 1

.LBB0_703:
	s_cmp_ge_u32 s12, 0x1000
	s_cbranch_scc1 .Lsp_4
	s_setprio 1

.LBB0_888:
	s_cmp_ge_u32 s23, 0x1000
	s_cbranch_scc1 .Lsp_5
	s_setprio 1
